# adaLN-norm output h stored write-through (sc0 sc1): consumed next phase by other XCDs, shortens the release at the seam; on top of f32-MFMA prologue fold
# speedup vs baseline: 1.0528x; 1.0013x over previous
; __device__ __forceinline__ int obid() { int b = (int)blockIdx.x; asm volatile("" : "+s"(b)); return b; }
; __device__ __forceinline__ void ph_norm(const Params& p_, int l, int skip_blocks) {
;     ...
;         for (int pi = (obid() - skip_blocks) * 8 + wave; pi >= 0 && pi < 4096; pi += nw) {
;             const int row = (pi >> 11) * 4096 + (pi & 2047);
;             const f32x4* xr0 = (const f32x4*)(xin + (size_t)row * DM) + lane; const f32x4* xr1 = (const f32x4*)(xin + (size_t)(row + stride) * DM) + lane;
;             const float* md = mod + (size_t)(l * 2 + (row >> 12)) * 6144;
;             f32x4 v0[8], v1[8], ca[8], cb[8];
; #pragma unroll
;             for (int j = 0; j < 8; ++j) { v0[j] = xr0[64 * j]; v1[j] = xr1[64 * j]; }
; #pragma unroll
;             for (int j = 0; j < 8; ++j) { const int col = (64 * j + lane) * 4; ca[j] = *(const f32x4*)(g + col) * (*(const f32x4*)(md + 2048 + col) + 1.f); cb[j] = *(const f32x4*)(md + col); }
;             asm volatile("" ::: "memory");
.LBB0_204:
	v_and_b32_e32 v0, 0x7ff, v197
	v_and_or_b32 v200, v198, s74, v0
	v_lshlrev_b32_e32 v0, 13, v200
	v_lshl_or_b32 v199, v200, 11, v181
	v_lshl_add_u64 v[2:3], v[98:99], 0, v[0:1]
	v_lshlrev_b32_e32 v0, 2, v199
	v_lshl_add_u64 v[4:5], v[98:99], 0, v[0:1]
	v_lshrrev_b32_e32 v0, 11, v197
	v_or_b32_e32 v0, s3, v0
	v_mul_u32_u24_e32 v0, 0x1800, v0
	global_load_dwordx4 v[62:65], v[2:3], off
	global_load_dwordx4 v[58:61], v[4:5], off
	global_load_dwordx4 v[54:57], v[2:3], off offset:1024
	global_load_dwordx4 v[50:53], v[4:5], off offset:1024
	global_load_dwordx4 v[46:49], v[2:3], off offset:2048
	global_load_dwordx4 v[42:45], v[4:5], off offset:2048
	global_load_dwordx4 v[38:41], v[2:3], off offset:3072
	global_load_dwordx4 v[34:37], v[4:5], off offset:3072
	v_add_co_u32_e32 v2, vcc, s74, v2
	v_lshl_add_u64 v[94:95], v[0:1], 2, s[42:43]
	s_nop 0
	v_addc_co_u32_e32 v3, vcc, 0, v3, vcc
	v_add_co_u32_e32 v4, vcc, s74, v4
	v_lshl_add_u64 v[96:97], v[94:95], 0, s[26:27]
	v_mov_b32_e32 v113, v1
	v_addc_co_u32_e32 v5, vcc, 0, v5, vcc
	v_lshl_add_u64 v[70:71], v[96:97], 0, v[112:113]
	global_load_dwordx4 v[30:33], v[2:3], off
	global_load_dwordx4 v[26:29], v[4:5], off
	global_load_dwordx4 v[22:25], v[2:3], off offset:1024
	global_load_dwordx4 v[18:21], v[4:5], off offset:1024
	global_load_dwordx4 v[14:17], v[2:3], off offset:2048
	global_load_dwordx4 v[10:13], v[4:5], off offset:2048
	global_load_dwordx4 v[6:9], v[2:3], off offset:3072
	s_nop 0
	global_load_dwordx4 v[2:5], v[4:5], off offset:3072
	v_mov_b32_e32 v115, v1
	global_load_dwordx4 v[70:73], v[70:71], off
	v_lshl_add_u64 v[86:87], v[94:95], 0, v[112:113]
	global_load_dwordx4 v[66:69], v[100:101], off
	v_lshl_add_u64 v[74:75], v[96:97], 0, v[114:115]
	v_mov_b32_e32 v117, v1
	v_lshl_add_u64 v[78:79], v[96:97], 0, v[116:117]
	v_mov_b32_e32 v119, v1
	v_lshl_add_u64 v[82:83], v[96:97], 0, v[118:119]
	v_mov_b32_e32 v121, v1
	v_mov_b32_e32 v123, v1
	v_lshl_add_u64 v[90:91], v[96:97], 0, v[122:123]
	v_mov_b32_e32 v125, v1
	v_lshl_add_u64 v[166:167], v[96:97], 0, v[124:125]
	v_mov_b32_e32 v127, v1
	v_xor_b32_e32 v119, 8, v178
	s_mov_b32 s12, 0x3a000000
	s_movk_i32 s9, 0xfff
	v_add_u32_e32 v198, s24, v198
	s_waitcnt vmcnt(0)
	v_mul_f32_e32 v0, v30, v30
	v_mul_f32_e32 v113, v31, v31
	v_mul_f32_e32 v115, v32, v32
	v_pk_add_f32 v[72:73], v[72:73], 1.0 op_sel_hi:[1,0]
	v_pk_add_f32 v[70:71], v[70:71], 1.0 op_sel_hi:[1,0]
	v_pk_mul_f32 v[128:129], v[68:69], v[72:73]
	v_pk_mul_f32 v[130:131], v[66:67], v[70:71]
	global_load_dwordx4 v[66:69], v[86:87], off
	global_load_dwordx4 v[70:73], v[100:101], off offset:1024
	v_mul_f32_e32 v117, v33, v33
	global_load_dwordx4 v[74:77], v[74:75], off
	s_waitcnt vmcnt(0)
	v_pk_add_f32 v[76:77], v[76:77], 1.0 op_sel_hi:[1,0]
	v_pk_add_f32 v[74:75], v[74:75], 1.0 op_sel_hi:[1,0]
	v_pk_mul_f32 v[132:133], v[72:73], v[76:77]
	v_pk_mul_f32 v[134:135], v[70:71], v[74:75]
	global_load_dwordx4 v[70:73], v[86:87], off offset:1024
	global_load_dwordx4 v[74:77], v[100:101], off offset:2048
	s_nop 0
	global_load_dwordx4 v[78:81], v[78:79], off
	s_waitcnt vmcnt(0)
	v_pk_add_f32 v[80:81], v[80:81], 1.0 op_sel_hi:[1,0]
	v_pk_add_f32 v[78:79], v[78:79], 1.0 op_sel_hi:[1,0]
	v_pk_mul_f32 v[136:137], v[76:77], v[80:81]
	v_pk_mul_f32 v[138:139], v[74:75], v[78:79]
	global_load_dwordx4 v[74:77], v[86:87], off offset:2048
	global_load_dwordx4 v[78:81], v[100:101], off offset:3072
	s_nop 0
	global_load_dwordx4 v[82:85], v[82:83], off
	s_waitcnt vmcnt(0)
	v_pk_add_f32 v[84:85], v[84:85], 1.0 op_sel_hi:[1,0]
	v_pk_add_f32 v[82:83], v[82:83], 1.0 op_sel_hi:[1,0]
	v_pk_mul_f32 v[140:141], v[80:81], v[84:85]
	v_pk_mul_f32 v[142:143], v[78:79], v[82:83]
	global_load_dwordx4 v[78:81], v[86:87], off offset:3072
	global_load_dwordx4 v[82:85], v[102:103], off
	v_lshl_add_u64 v[86:87], v[96:97], 0, v[120:121]
	global_load_dwordx4 v[86:89], v[86:87], off
	v_lshl_add_u64 v[96:97], v[96:97], 0, v[126:127]
	s_waitcnt vmcnt(0)
	v_pk_add_f32 v[86:87], v[86:87], 1.0 op_sel_hi:[1,0]
	v_pk_add_f32 v[88:89], v[88:89], 1.0 op_sel_hi:[1,0]
	v_pk_mul_f32 v[160:161], v[82:83], v[86:87]
	v_lshl_add_u64 v[82:83], v[94:95], 0, v[120:121]
	v_pk_mul_f32 v[144:145], v[84:85], v[88:89]
	global_load_dwordx4 v[82:85], v[82:83], off
	s_nop 0
	global_load_dwordx4 v[86:89], v[104:105], off
	v_xor_b32_e32 v121, 16, v178
	global_load_dwordx4 v[90:93], v[90:91], off
	s_waitcnt vmcnt(0)
	v_pk_add_f32 v[90:91], v[90:91], 1.0 op_sel_hi:[1,0]
	v_pk_add_f32 v[92:93], v[92:93], 1.0 op_sel_hi:[1,0]
	v_pk_mul_f32 v[164:165], v[86:87], v[90:91]
	v_lshl_add_u64 v[86:87], v[94:95], 0, v[122:123]
	v_pk_mul_f32 v[162:163], v[88:89], v[92:93]
	global_load_dwordx4 v[86:89], v[86:87], off
	s_nop 0
	global_load_dwordx4 v[90:93], v[106:107], off
	v_xor_b32_e32 v123, 32, v178
	global_load_dwordx4 v[166:169], v[166:167], off
	s_waitcnt vmcnt(0)
	v_pk_add_f32 v[168:169], v[168:169], 1.0 op_sel_hi:[1,0]
	v_pk_add_f32 v[170:171], v[166:167], 1.0 op_sel_hi:[1,0]
	v_pk_mul_f32 v[166:167], v[92:93], v[168:169]
	v_pk_mul_f32 v[168:169], v[90:91], v[170:171]
	v_lshl_add_u64 v[90:91], v[94:95], 0, v[124:125]
	global_load_dwordx4 v[90:93], v[90:91], off
	s_nop 0
	global_load_dwordx4 v[172:175], v[108:109], off
	global_load_dwordx4 v[202:205], v[96:97], off
	v_lshl_add_u64 v[94:95], v[94:95], 0, v[126:127]
	s_waitcnt vmcnt(0)
; __device__ __forceinline__ void ph_norm(const Params& p_, int l, int skip_blocks) {
;     ...
;             float s0 = 0.f, s1 = 0.f;
; #pragma unroll
;             for (int j = 0; j < 8; ++j) { s0 += (v0[j][0] * v0[j][0] + v0[j][1] * v0[j][1]) + (v0[j][2] * v0[j][2] + v0[j][3] * v0[j][3]); s1 += (v1[j][0] * v1[j][0] + v1[j][1] * v1[j][1]) + (v1[j][2] * v1[j][2] + v1[j][3] * v1[j][3]); }
;             s0 = wave_sum(s0); s1 = wave_sum(s1);
	v_pk_add_f32 v[176:177], v[202:203], 1.0 op_sel_hi:[1,0]
	v_pk_add_f32 v[96:97], v[204:205], 1.0 op_sel_hi:[1,0]
	v_pk_mul_f32 v[172:173], v[172:173], v[176:177]
	v_mov_b32_e32 v176, v63
	v_mov_b32_e32 v177, v55
	v_pk_mul_f32 v[170:171], v[174:175], v[96:97]
	v_mov_b32_e32 v174, v62
	v_mov_b32_e32 v175, v54
	v_pk_mul_f32 v[176:177], v[176:177], v[176:177]
	v_mov_b32_e32 v202, v65
	v_mov_b32_e32 v203, v57
	v_pk_fma_f32 v[174:175], v[174:175], v[174:175], v[176:177]
	v_mov_b32_e32 v176, v64
	v_mov_b32_e32 v177, v56
	v_pk_mul_f32 v[202:203], v[202:203], v[202:203]
	v_mov_b32_e32 v204, v61
	v_pk_fma_f32 v[176:177], v[176:177], v[176:177], v[202:203]
	v_mov_b32_e32 v202, v59
	v_mov_b32_e32 v203, v51
	v_pk_add_f32 v[174:175], v[174:175], v[176:177]
	v_mov_b32_e32 v176, v58
	v_mov_b32_e32 v177, v50
	v_pk_mul_f32 v[202:203], v[202:203], v[202:203]
	v_mov_b32_e32 v205, v53
	v_pk_fma_f32 v[176:177], v[176:177], v[176:177], v[202:203]
	v_mov_b32_e32 v202, v60
	v_mov_b32_e32 v203, v52
	v_pk_mul_f32 v[204:205], v[204:205], v[204:205]
	v_pk_add_f32 v[174:175], v[174:175], v[174:175] op_sel:[0,1] op_sel_hi:[1,0]
	v_pk_fma_f32 v[202:203], v[202:203], v[202:203], v[204:205]
	v_pk_mul_f32 v[204:205], v[46:47], v[46:47]
	v_pk_add_f32 v[176:177], v[176:177], v[202:203]
	v_pk_mul_f32 v[202:203], v[48:49], v[48:49]
	v_mov_b32_e32 v175, v0
	v_pk_mov_b32 v[206:207], v[204:205], v[202:203] op_sel:[1,0]
	v_mov_b32_e32 v205, v203
	v_pk_add_f32 v[202:203], v[206:207], v[204:205]
	v_pk_mul_f32 v[204:205], v[44:45], v[44:45]
	v_pk_add_f32 v[202:203], v[202:203], v[202:203] op_sel:[0,1] op_sel_hi:[1,0]
	v_pk_mul_f32 v[206:207], v[42:43], v[42:43]
	v_mov_b32_e32 v203, v113
	v_mul_f32_e32 v0, v39, v39
	v_pk_mov_b32 v[208:209], v[206:207], v[204:205] op_sel:[1,0]
	v_mov_b32_e32 v207, v205
	v_pk_add_f32 v[174:175], v[174:175], v[202:203]
	v_pk_fma_f32 v[202:203], v[38:39], v[38:39], v[0:1] op_sel_hi:[1,1,0]
	v_mul_f32_e32 v0, v41, v41
	v_pk_add_f32 v[204:205], v[208:209], v[206:207]
	v_pk_fma_f32 v[206:207], v[40:41], v[40:41], v[0:1] op_sel_hi:[1,1,0]
	v_mov_b32_e32 v203, v115
	v_mov_b32_e32 v207, v117
	v_pk_add_f32 v[202:203], v[202:203], v[206:207]
	v_mul_f32_e32 v0, v26, v26
	v_pk_add_f32 v[174:175], v[174:175], v[202:203]
	v_mul_f32_e32 v113, v27, v27
	v_pk_add_f32 v[176:177], v[176:177], v[176:177] op_sel:[0,1] op_sel_hi:[1,0]
	v_pk_add_f32 v[202:203], v[204:205], v[204:205] op_sel:[0,1] op_sel_hi:[1,0]
	v_mov_b32_e32 v177, v0
	v_mov_b32_e32 v203, v113
	v_mul_f32_e32 v0, v35, v35
	v_pk_add_f32 v[176:177], v[176:177], v[202:203]
	v_pk_fma_f32 v[202:203], v[34:35], v[34:35], v[0:1] op_sel_hi:[1,1,0]
	v_mul_f32_e32 v0, v37, v37
	v_mul_f32_e32 v115, v28, v28
	v_mul_f32_e32 v117, v29, v29
	v_pk_fma_f32 v[204:205], v[36:37], v[36:37], v[0:1] op_sel_hi:[1,1,0]
	v_mov_b32_e32 v203, v115
	v_mov_b32_e32 v205, v117
	v_pk_add_f32 v[202:203], v[202:203], v[204:205]
	v_pk_mul_f32 v[204:205], v[22:23], v[22:23]
	v_pk_add_f32 v[176:177], v[176:177], v[202:203]
	v_pk_mul_f32 v[202:203], v[24:25], v[24:25]
	v_mul_f32_e32 v0, v6, v6
	v_pk_mov_b32 v[206:207], v[204:205], v[202:203] op_sel:[1,0]
	v_mov_b32_e32 v205, v203
	v_pk_add_f32 v[202:203], v[206:207], v[204:205]
	v_mul_f32_e32 v113, v7, v7
	v_pk_add_f32 v[174:175], v[174:175], v[174:175] op_sel:[0,1] op_sel_hi:[1,0]
	v_pk_add_f32 v[202:203], v[202:203], v[202:203] op_sel:[0,1] op_sel_hi:[1,0]
	v_pk_mul_f32 v[204:205], v[20:21], v[20:21]
	v_pk_mul_f32 v[206:207], v[18:19], v[18:19]
	v_mov_b32_e32 v175, v0
	v_mov_b32_e32 v203, v113
	v_mul_f32_e32 v0, v15, v15
	v_pk_mov_b32 v[208:209], v[206:207], v[204:205] op_sel:[1,0]
	v_mov_b32_e32 v207, v205
	v_pk_add_f32 v[174:175], v[174:175], v[202:203]
	v_pk_fma_f32 v[202:203], v[14:15], v[14:15], v[0:1] op_sel_hi:[1,1,0]
	v_mul_f32_e32 v0, v17, v17
	v_pk_add_f32 v[204:205], v[208:209], v[206:207]
	v_mul_f32_e32 v115, v8, v8
	v_mul_f32_e32 v117, v9, v9
	v_pk_fma_f32 v[206:207], v[16:17], v[16:17], v[0:1] op_sel_hi:[1,1,0]
	v_mov_b32_e32 v203, v115
	v_mov_b32_e32 v207, v117
	v_pk_add_f32 v[202:203], v[202:203], v[206:207]
	v_mul_f32_e32 v0, v2, v2
	v_pk_add_f32 v[174:175], v[174:175], v[202:203]
	v_mul_f32_e32 v113, v3, v3
	v_pk_add_f32 v[176:177], v[176:177], v[176:177] op_sel:[0,1] op_sel_hi:[1,0]
	v_pk_add_f32 v[202:203], v[204:205], v[204:205] op_sel:[0,1] op_sel_hi:[1,0]
	v_mov_b32_e32 v177, v0
	v_mov_b32_e32 v203, v113
	v_mul_f32_e32 v0, v11, v11
	v_pk_add_f32 v[176:177], v[176:177], v[202:203]
	v_pk_fma_f32 v[202:203], v[10:11], v[10:11], v[0:1] op_sel_hi:[1,1,0]
	v_mul_f32_e32 v0, v13, v13
	v_mul_f32_e32 v115, v4, v4
	v_mul_f32_e32 v117, v5, v5
	v_pk_fma_f32 v[204:205], v[12:13], v[12:13], v[0:1] op_sel_hi:[1,1,0]
	v_mov_b32_e32 v203, v115
	v_mov_b32_e32 v205, v117
	v_and_b32_e32 v0, 64, v178
	v_pk_add_f32 v[202:203], v[202:203], v[204:205]
	v_add_u32_e32 v0, 64, v0
	v_xor_b32_e32 v113, 1, v178
	v_pk_add_f32 v[176:177], v[176:177], v[202:203]
	v_cmp_lt_i32_e32 vcc, v113, v0
	v_mov_b32_e32 v202, v176
	v_mov_b32_e32 v203, v174
	v_cndmask_b32_e32 v113, v178, v113, vcc
	v_mov_b32_e32 v174, v177
	v_lshlrev_b32_e32 v113, 2, v113
	v_pk_add_f32 v[174:175], v[202:203], v[174:175]
	ds_bpermute_b32 v177, v113, v175
	ds_bpermute_b32 v176, v113, v174
	v_xor_b32_e32 v115, 2, v178
	v_cmp_lt_i32_e32 vcc, v115, v0
	v_xor_b32_e32 v117, 4, v178
	global_load_dwordx4 v[94:97], v[94:95], off
	v_cndmask_b32_e32 v115, v178, v115, vcc
	v_lshlrev_b32_e32 v115, 2, v115
	s_waitcnt lgkmcnt(0)
	v_pk_add_f32 v[174:175], v[174:175], v[176:177]
	ds_bpermute_b32 v177, v115, v175
	ds_bpermute_b32 v176, v115, v174
	v_cmp_lt_i32_e32 vcc, v117, v0
	s_waitcnt lgkmcnt(0)
; __device__ __forceinline__ unsigned pk2(float lo, float hi) { return f2bf(lo) | (f2bf(hi) << 16); }
; __device__ __forceinline__ void ph_norm(const Params& p_, int l, int skip_blocks) {
;     ...
;             s0 = wave_sum(s0); s1 = wave_sum(s1);
;             const float r0 = rsqrtf(s0 * (1.f / DM) + 1e-6f), r1 = rsqrtf(s1 * (1.f / DM) + 1e-6f);
; #pragma unroll
;             for (int j = 0; j < 8; ++j) { const int col = (64 * j + lane) * 4;
;                 const f32x4 o0 = (v0[j] * r0) * ca[j] + cb[j], o1 = (v1[j] * r1) * ca[j] + cb[j]; u32x2 w;
;                 w.x = pk2(o0[0], o0[1]); w.y = pk2(o0[2], o0[3]); *(u32x2*)(h + (size_t)row * DM + col) = w;
;                 w.x = pk2(o1[0], o1[1]); w.y = pk2(o1[2], o1[3]); *(u32x2*)(h + (size_t)(row + stride) * DM + col) = w; }
	v_pk_add_f32 v[174:175], v[174:175], v[176:177]
	v_cndmask_b32_e32 v117, v178, v117, vcc
	v_lshlrev_b32_e32 v117, 2, v117
	ds_bpermute_b32 v177, v117, v175
	ds_bpermute_b32 v176, v117, v174
	v_cmp_lt_i32_e32 vcc, v119, v0
	s_waitcnt lgkmcnt(0)
	v_pk_add_f32 v[174:175], v[174:175], v[176:177]
	v_cndmask_b32_e32 v119, v178, v119, vcc
	v_lshlrev_b32_e32 v119, 2, v119
	ds_bpermute_b32 v177, v119, v175
	ds_bpermute_b32 v176, v119, v174
	v_cmp_lt_i32_e32 vcc, v121, v0
	s_waitcnt lgkmcnt(0)
	v_pk_add_f32 v[174:175], v[174:175], v[176:177]
	v_cndmask_b32_e32 v121, v178, v121, vcc
	v_lshlrev_b32_e32 v121, 2, v121
	ds_bpermute_b32 v177, v121, v175
	ds_bpermute_b32 v176, v121, v174
	v_cmp_lt_i32_e32 vcc, v123, v0
	s_waitcnt lgkmcnt(0)
	v_pk_add_f32 v[174:175], v[174:175], v[176:177]
	v_cndmask_b32_e32 v0, v178, v123, vcc
	v_lshlrev_b32_e32 v0, 2, v0
	ds_bpermute_b32 v177, v0, v175
	ds_bpermute_b32 v176, v0, v174
	s_waitcnt lgkmcnt(0)
	v_pk_add_f32 v[174:175], v[174:175], v[176:177]
	s_nop 0
	v_pk_fma_f32 v[174:175], v[174:175], s[12:13], v[146:147] op_sel_hi:[1,0,0]
	s_nop 0
	v_mul_f32_e32 v0, 0x4b800000, v175
	v_cmp_gt_f32_e64 s[36:37], s92, v175
	v_cmp_gt_f32_e32 vcc, s92, v174
	s_nop 0
	v_cndmask_b32_e64 v0, v175, v0, s[36:37]
	v_rsq_f32_e32 v0, v0
	s_nop 0
	v_mul_f32_e32 v113, 0x45800000, v0
	v_cndmask_b32_e64 v176, v0, v113, s[36:37]
	v_mul_f32_e32 v0, 0x4b800000, v174
	v_cndmask_b32_e32 v0, v174, v0, vcc
	v_rsq_f32_e32 v0, v0
	v_pk_mul_f32 v[62:63], v[62:63], v[176:177] op_sel_hi:[1,0]
	v_pk_mul_f32 v[64:65], v[64:65], v[176:177] op_sel_hi:[1,0]
	v_pk_fma_f32 v[62:63], v[130:131], v[62:63], v[66:67]
	v_mul_f32_e32 v113, 0x45800000, v0
	v_cndmask_b32_e32 v174, v0, v113, vcc
	v_bfe_u32 v0, v62, 16, 1
	v_add3_u32 v0, v62, v0, s14
	v_bfe_u32 v62, v63, 16, 1
	v_pk_fma_f32 v[64:65], v[128:129], v[64:65], v[68:69]
	v_lshrrev_b32_e32 v0, 16, v0
	v_add3_u32 v62, v63, v62, s14
	v_and_or_b32 v62, v62, s15, v0
	v_bfe_u32 v0, v64, 16, 1
	v_add3_u32 v0, v64, v0, s14
	v_bfe_u32 v63, v65, 16, 1
	v_pk_mul_f32 v[58:59], v[58:59], v[174:175] op_sel_hi:[1,0]
	v_lshrrev_b32_e32 v0, 16, v0
	v_add3_u32 v63, v65, v63, s14
	v_pk_fma_f32 v[58:59], v[130:131], v[58:59], v[66:67]
	v_and_or_b32 v63, v63, s15, v0
	v_lshlrev_b32_e32 v0, 12, v200
	v_lshl_add_u64 v[64:65], v[110:111], 0, v[0:1]
	v_bfe_u32 v0, v58, 16, 1
	v_pk_mul_f32 v[60:61], v[60:61], v[174:175] op_sel_hi:[1,0]
	v_add3_u32 v0, v58, v0, s14
	v_bfe_u32 v58, v59, 16, 1
	v_pk_fma_f32 v[60:61], v[128:129], v[60:61], v[68:69]
	v_lshrrev_b32_e32 v0, 16, v0
	v_add3_u32 v58, v59, v58, s14
	v_and_or_b32 v58, v58, s15, v0
	v_bfe_u32 v0, v60, 16, 1
	v_add3_u32 v0, v60, v0, s14
	v_bfe_u32 v59, v61, 16, 1
	v_lshrrev_b32_e32 v0, 16, v0
	v_add3_u32 v59, v61, v59, s14
	v_pk_mul_f32 v[54:55], v[54:55], v[176:177] op_sel_hi:[1,0]
	v_and_or_b32 v59, v59, s15, v0
	v_lshlrev_b32_e32 v0, 1, v199
	v_pk_fma_f32 v[54:55], v[134:135], v[54:55], v[70:71]
	v_lshl_add_u64 v[60:61], v[110:111], 0, v[0:1]
	v_bfe_u32 v0, v54, 16, 1
	v_pk_mul_f32 v[56:57], v[56:57], v[176:177] op_sel_hi:[1,0]
	v_add3_u32 v0, v54, v0, s14
	v_bfe_u32 v54, v55, 16, 1
	v_pk_fma_f32 v[56:57], v[132:133], v[56:57], v[72:73]
	v_lshrrev_b32_e32 v0, 16, v0
	v_add3_u32 v54, v55, v54, s14
	v_and_or_b32 v54, v54, s15, v0
	v_bfe_u32 v0, v56, 16, 1
	v_pk_mul_f32 v[50:51], v[50:51], v[174:175] op_sel_hi:[1,0]
	v_add3_u32 v0, v56, v0, s14
	v_bfe_u32 v55, v57, 16, 1
	v_pk_fma_f32 v[50:51], v[134:135], v[50:51], v[70:71]
	v_lshrrev_b32_e32 v0, 16, v0
	v_add3_u32 v55, v57, v55, s14
	v_and_or_b32 v55, v55, s15, v0
	v_bfe_u32 v0, v50, 16, 1
	v_pk_mul_f32 v[52:53], v[52:53], v[174:175] op_sel_hi:[1,0]
	v_add3_u32 v0, v50, v0, s14
	v_bfe_u32 v50, v51, 16, 1
	v_pk_fma_f32 v[52:53], v[132:133], v[52:53], v[72:73]
	v_lshrrev_b32_e32 v0, 16, v0
	v_add3_u32 v50, v51, v50, s14
	v_and_or_b32 v50, v50, s15, v0
	v_bfe_u32 v0, v52, 16, 1
	v_add3_u32 v0, v52, v0, s14
	v_bfe_u32 v51, v53, 16, 1
	v_pk_mul_f32 v[46:47], v[46:47], v[176:177] op_sel_hi:[1,0]
	v_lshrrev_b32_e32 v0, 16, v0
	v_add3_u32 v51, v53, v51, s14
	v_pk_fma_f32 v[46:47], v[138:139], v[46:47], v[74:75]
	v_and_or_b32 v51, v51, s15, v0
	v_bfe_u32 v0, v46, 16, 1
	v_pk_mul_f32 v[48:49], v[48:49], v[176:177] op_sel_hi:[1,0]
	v_add3_u32 v0, v46, v0, s14
	v_bfe_u32 v46, v47, 16, 1
	v_pk_fma_f32 v[48:49], v[136:137], v[48:49], v[76:77]
	v_lshrrev_b32_e32 v0, 16, v0
	v_add3_u32 v46, v47, v46, s14
	v_and_or_b32 v46, v46, s15, v0
	v_bfe_u32 v0, v48, 16, 1
	v_pk_mul_f32 v[42:43], v[42:43], v[174:175] op_sel_hi:[1,0]
	v_add3_u32 v0, v48, v0, s14
	v_bfe_u32 v47, v49, 16, 1
	v_pk_fma_f32 v[42:43], v[138:139], v[42:43], v[74:75]
	v_lshrrev_b32_e32 v0, 16, v0
	v_add3_u32 v47, v49, v47, s14
	v_and_or_b32 v47, v47, s15, v0
	v_bfe_u32 v0, v42, 16, 1
	v_pk_mul_f32 v[44:45], v[44:45], v[174:175] op_sel_hi:[1,0]
	v_add3_u32 v0, v42, v0, s14
	v_bfe_u32 v42, v43, 16, 1
	v_pk_fma_f32 v[44:45], v[136:137], v[44:45], v[76:77]
	v_lshrrev_b32_e32 v0, 16, v0
	v_add3_u32 v42, v43, v42, s14
	v_and_or_b32 v42, v42, s15, v0
	v_bfe_u32 v0, v44, 16, 1
	v_add3_u32 v0, v44, v0, s14
	v_bfe_u32 v43, v45, 16, 1
	v_pk_mul_f32 v[38:39], v[38:39], v[176:177] op_sel_hi:[1,0]
	v_lshrrev_b32_e32 v0, 16, v0
	v_add3_u32 v43, v45, v43, s14
	v_pk_fma_f32 v[38:39], v[142:143], v[38:39], v[78:79]
	v_and_or_b32 v43, v43, s15, v0
	v_bfe_u32 v0, v38, 16, 1
	v_pk_mul_f32 v[40:41], v[40:41], v[176:177] op_sel_hi:[1,0]
	v_add3_u32 v0, v38, v0, s14
	v_bfe_u32 v38, v39, 16, 1
	v_pk_fma_f32 v[40:41], v[140:141], v[40:41], v[80:81]
	v_lshrrev_b32_e32 v0, 16, v0
	v_add3_u32 v38, v39, v38, s14
	v_and_or_b32 v38, v38, s15, v0
	v_bfe_u32 v0, v40, 16, 1
	v_pk_mul_f32 v[34:35], v[34:35], v[174:175] op_sel_hi:[1,0]
; __device__ __forceinline__ unsigned pk2(float lo, float hi) { return f2bf(lo) | (f2bf(hi) << 16); }
; __device__ __forceinline__ void ph_norm(const Params& p_, int l, int skip_blocks) {
;     ...
; #pragma unroll
;             for (int j = 0; j < 8; ++j) { const int col = (64 * j + lane) * 4;
;                 const f32x4 o0 = (v0[j] * r0) * ca[j] + cb[j], o1 = (v1[j] * r1) * ca[j] + cb[j]; u32x2 w;
;                 w.x = pk2(o0[0], o0[1]); w.y = pk2(o0[2], o0[3]); *(u32x2*)(h + (size_t)row * DM + col) = w;
;                 w.x = pk2(o1[0], o1[1]); w.y = pk2(o1[2], o1[3]); *(u32x2*)(h + (size_t)(row + stride) * DM + col) = w; }
	v_add3_u32 v0, v40, v0, s14
	v_bfe_u32 v39, v41, 16, 1
	v_pk_fma_f32 v[34:35], v[142:143], v[34:35], v[78:79]
	v_lshrrev_b32_e32 v0, 16, v0
	v_add3_u32 v39, v41, v39, s14
	v_and_or_b32 v39, v39, s15, v0
	v_bfe_u32 v0, v34, 16, 1
	v_pk_mul_f32 v[36:37], v[36:37], v[174:175] op_sel_hi:[1,0]
	v_add3_u32 v0, v34, v0, s14
	v_bfe_u32 v34, v35, 16, 1
	v_pk_fma_f32 v[36:37], v[140:141], v[36:37], v[80:81]
	v_lshrrev_b32_e32 v0, 16, v0
	v_add3_u32 v34, v35, v34, s14
	v_and_or_b32 v34, v34, s15, v0
	v_bfe_u32 v0, v36, 16, 1
	v_add3_u32 v0, v36, v0, s14
	v_bfe_u32 v35, v37, 16, 1
	v_pk_mul_f32 v[30:31], v[30:31], v[176:177] op_sel_hi:[1,0]
	v_lshrrev_b32_e32 v0, 16, v0
	v_add3_u32 v35, v37, v35, s14
	v_pk_fma_f32 v[30:31], v[160:161], v[30:31], v[82:83]
	v_and_or_b32 v35, v35, s15, v0
	v_bfe_u32 v0, v30, 16, 1
	v_pk_mul_f32 v[32:33], v[32:33], v[176:177] op_sel_hi:[1,0]
	v_add3_u32 v0, v30, v0, s14
	v_bfe_u32 v30, v31, 16, 1
	v_pk_fma_f32 v[32:33], v[144:145], v[32:33], v[84:85]
	v_lshrrev_b32_e32 v0, 16, v0
	v_add3_u32 v30, v31, v30, s14
	v_and_or_b32 v30, v30, s15, v0
	v_bfe_u32 v0, v32, 16, 1
	v_pk_mul_f32 v[26:27], v[26:27], v[174:175] op_sel_hi:[1,0]
	v_add3_u32 v0, v32, v0, s14
	v_bfe_u32 v31, v33, 16, 1
	v_pk_fma_f32 v[26:27], v[160:161], v[26:27], v[82:83]
	v_lshrrev_b32_e32 v0, 16, v0
	v_add3_u32 v31, v33, v31, s14
	v_and_or_b32 v31, v31, s15, v0
	v_bfe_u32 v0, v26, 16, 1
	v_pk_mul_f32 v[28:29], v[28:29], v[174:175] op_sel_hi:[1,0]
	v_add3_u32 v0, v26, v0, s14
	v_bfe_u32 v26, v27, 16, 1
	v_pk_fma_f32 v[28:29], v[144:145], v[28:29], v[84:85]
	v_lshrrev_b32_e32 v0, 16, v0
	v_add3_u32 v26, v27, v26, s14
	v_and_or_b32 v26, v26, s15, v0
	v_bfe_u32 v0, v28, 16, 1
	v_add3_u32 v0, v28, v0, s14
	v_bfe_u32 v27, v29, 16, 1
	v_pk_mul_f32 v[22:23], v[22:23], v[176:177] op_sel_hi:[1,0]
	v_lshrrev_b32_e32 v0, 16, v0
	v_add3_u32 v27, v29, v27, s14
	v_pk_fma_f32 v[22:23], v[164:165], v[22:23], v[86:87]
	v_and_or_b32 v27, v27, s15, v0
	v_bfe_u32 v0, v22, 16, 1
	v_pk_mul_f32 v[24:25], v[24:25], v[176:177] op_sel_hi:[1,0]
	v_add3_u32 v0, v22, v0, s14
	v_bfe_u32 v22, v23, 16, 1
	v_pk_fma_f32 v[24:25], v[162:163], v[24:25], v[88:89]
	v_lshrrev_b32_e32 v0, 16, v0
	v_add3_u32 v22, v23, v22, s14
	v_and_or_b32 v22, v22, s15, v0
	v_bfe_u32 v0, v24, 16, 1
	v_pk_mul_f32 v[18:19], v[18:19], v[174:175] op_sel_hi:[1,0]
	v_add3_u32 v0, v24, v0, s14
	v_bfe_u32 v23, v25, 16, 1
	v_pk_fma_f32 v[18:19], v[164:165], v[18:19], v[86:87]
	v_lshrrev_b32_e32 v0, 16, v0
	v_add3_u32 v23, v25, v23, s14
	v_and_or_b32 v23, v23, s15, v0
	v_bfe_u32 v0, v18, 16, 1
	v_pk_mul_f32 v[20:21], v[20:21], v[174:175] op_sel_hi:[1,0]
	v_add3_u32 v0, v18, v0, s14
	v_bfe_u32 v18, v19, 16, 1
	v_pk_fma_f32 v[20:21], v[162:163], v[20:21], v[88:89]
	v_lshrrev_b32_e32 v0, 16, v0
	v_add3_u32 v18, v19, v18, s14
	v_and_or_b32 v18, v18, s15, v0
	v_bfe_u32 v0, v20, 16, 1
	v_add3_u32 v0, v20, v0, s14
	v_bfe_u32 v19, v21, 16, 1
	v_pk_mul_f32 v[14:15], v[14:15], v[176:177] op_sel_hi:[1,0]
	v_lshrrev_b32_e32 v0, 16, v0
	v_add3_u32 v19, v21, v19, s14
	v_pk_fma_f32 v[14:15], v[168:169], v[14:15], v[90:91]
	v_and_or_b32 v19, v19, s15, v0
	v_bfe_u32 v0, v14, 16, 1
	v_pk_mul_f32 v[16:17], v[16:17], v[176:177] op_sel_hi:[1,0]
	v_add3_u32 v0, v14, v0, s14
	v_bfe_u32 v14, v15, 16, 1
	v_pk_fma_f32 v[16:17], v[166:167], v[16:17], v[92:93]
	v_lshrrev_b32_e32 v0, 16, v0
	v_add3_u32 v14, v15, v14, s14
	v_and_or_b32 v14, v14, s15, v0
	v_bfe_u32 v0, v16, 16, 1
	v_pk_mul_f32 v[10:11], v[10:11], v[174:175] op_sel_hi:[1,0]
	v_add3_u32 v0, v16, v0, s14
	v_bfe_u32 v15, v17, 16, 1
	v_pk_fma_f32 v[10:11], v[168:169], v[10:11], v[90:91]
	v_lshrrev_b32_e32 v0, 16, v0
	v_add3_u32 v15, v17, v15, s14
	v_and_or_b32 v15, v15, s15, v0
	v_bfe_u32 v0, v10, 16, 1
	v_pk_mul_f32 v[12:13], v[12:13], v[174:175] op_sel_hi:[1,0]
	v_add3_u32 v0, v10, v0, s14
	v_bfe_u32 v10, v11, 16, 1
	v_pk_fma_f32 v[12:13], v[166:167], v[12:13], v[92:93]
	v_lshrrev_b32_e32 v0, 16, v0
	v_add3_u32 v10, v11, v10, s14
	v_and_or_b32 v10, v10, s15, v0
	v_bfe_u32 v0, v12, 16, 1
	v_add3_u32 v0, v12, v0, s14
	v_bfe_u32 v11, v13, 16, 1
	v_pk_mul_f32 v[6:7], v[6:7], v[176:177] op_sel_hi:[1,0]
	v_lshrrev_b32_e32 v0, 16, v0
	v_add3_u32 v11, v13, v11, s14
	s_waitcnt vmcnt(0)
	v_pk_fma_f32 v[6:7], v[172:173], v[6:7], v[94:95]
	v_and_or_b32 v11, v11, s15, v0
	v_bfe_u32 v0, v6, 16, 1
	v_pk_mul_f32 v[8:9], v[8:9], v[176:177] op_sel_hi:[1,0]
	v_add3_u32 v0, v6, v0, s14
	v_bfe_u32 v6, v7, 16, 1
	v_pk_fma_f32 v[8:9], v[170:171], v[8:9], v[96:97]
	v_lshrrev_b32_e32 v0, 16, v0
	v_add3_u32 v6, v7, v6, s14
	v_and_or_b32 v6, v6, s15, v0
	v_bfe_u32 v0, v8, 16, 1
	v_pk_mul_f32 v[2:3], v[2:3], v[174:175] op_sel_hi:[1,0]
	v_add3_u32 v0, v8, v0, s14
	v_bfe_u32 v7, v9, 16, 1
	v_pk_fma_f32 v[2:3], v[172:173], v[2:3], v[94:95]
	v_lshrrev_b32_e32 v0, 16, v0
	v_add3_u32 v7, v9, v7, s14
	v_and_or_b32 v7, v7, s15, v0
	v_bfe_u32 v0, v2, 16, 1
	v_pk_mul_f32 v[4:5], v[4:5], v[174:175] op_sel_hi:[1,0]
	v_add3_u32 v0, v2, v0, s14
	v_bfe_u32 v2, v3, 16, 1
	v_pk_fma_f32 v[4:5], v[170:171], v[4:5], v[96:97]
	v_lshrrev_b32_e32 v0, 16, v0
	v_add3_u32 v2, v3, v2, s14
	v_and_or_b32 v2, v2, s15, v0
	v_bfe_u32 v0, v4, 16, 1
	v_add3_u32 v0, v4, v0, s14
	v_bfe_u32 v3, v5, 16, 1
	v_lshrrev_b32_e32 v0, 16, v0
	v_add3_u32 v3, v5, v3, s14
	v_and_or_b32 v3, v3, s15, v0
	v_subrev_u32_e32 v0, s10, v197
	v_add_u32_e32 v197, 0x800, v0
	v_cmp_lt_u32_e32 vcc, s9, v197
	s_or_b64 s[46:47], vcc, s[46:47]
	global_store_dwordx2 v[64:65], v[62:63], off sc0 sc1
	global_store_dwordx2 v[60:61], v[58:59], off sc0 sc1
	global_store_dwordx2 v[64:65], v[54:55], off offset:512 sc0 sc1
	global_store_dwordx2 v[60:61], v[50:51], off offset:512 sc0 sc1
	global_store_dwordx2 v[64:65], v[46:47], off offset:1024 sc0 sc1
	global_store_dwordx2 v[60:61], v[42:43], off offset:1024 sc0 sc1
	global_store_dwordx2 v[64:65], v[38:39], off offset:1536 sc0 sc1
	global_store_dwordx2 v[60:61], v[34:35], off offset:1536 sc0 sc1
	global_store_dwordx2 v[64:65], v[30:31], off offset:2048 sc0 sc1
	global_store_dwordx2 v[60:61], v[26:27], off offset:2048 sc0 sc1
	global_store_dwordx2 v[64:65], v[22:23], off offset:2560 sc0 sc1
	global_store_dwordx2 v[60:61], v[18:19], off offset:2560 sc0 sc1
	global_store_dwordx2 v[64:65], v[14:15], off offset:3072 sc0 sc1
	global_store_dwordx2 v[60:61], v[10:11], off offset:3072 sc0 sc1
	global_store_dwordx2 v[64:65], v[6:7], off offset:3584 sc0 sc1
	global_store_dwordx2 v[60:61], v[2:3], off offset:3584 sc0 sc1
	s_andn2_b64 exec, exec, s[46:47]
	s_cbranch_execnz .LBB0_204
